# merge k-loop: A fragments double-buffered (second buffer freed by landing the last gate quad in two register pairs), second k-step B fragments reloaded behind their last use
# speedup vs baseline: 1.0120x; 1.0120x over previous
; #define ZERO_ACC(acc)                                  \
;   _Pragma("unroll") for (int i_ = 0; i_ < 4; ++i_)     \
;   _Pragma("unroll") for (int j_ = 0; j_ < 4; ++j_) { acc[i_][j_] = (f32x4){0.f, 0.f, 0.f, 0.f}; }
; template <int MI, int NJ> ...
;     ...
;   if (!pre) G8LOADP(Ag, Bg);
;   G8STORE(0);
;   {
;     const u16* ga_ = (1 < nk) ? Ag + 64 : Ag + nAoff;
;     const u16* gb_ = (1 < nk) ? Bg + 64 : Bg + nBoff;
;     G8LOADP(ga_, gb_);
;   }
;   __syncthreads();
; __device__ __forceinline__ void phase_merge(const Params& p, u16* smem, volatile LAS unsigned* vb_) {
;     ...
;     for (int n = 0; n < 3; ++n) {
;       f32x4 acc[4][4];
;       ZERO_ACC(acc);
;       gemm8<4, 4>(acc, G8REGS_ARGS, pre, Y, 1536, W, 1536, n * 512, n * 512 + 512, mt * 128, nt * 256,
;                   (n < 2) ? mt * 128 : nmt * 128, (n < 2) ? nt * 256 : nnt * 256, (n < 2) ? (n + 1) * 512 : 0, smem, tid);
;     ...
;       for (int k = 0; k < 8; ++k) {
;         const int c = tid2 + 512 * k;
;         const int row = c >> 5, ch = c & 31;
;         *(uint4*)(smem + row * 264 + ch * 8) = *(const uint4*)(MG + (size_t)(mt * 128 + row) * 3072 + n * 1024 + nt * 256 + ch * 8);
;       }
.LBB0_25:
	s_lshl_b32 s13, s39, 9
	s_waitcnt vmcnt(5)
	ds_write_b128 v183, v[2:5]
	s_waitcnt vmcnt(3)
	ds_write_b128 v183, v[10:13] offset:8192
	ds_write_b128 v183, v[6:9] offset:32768
	s_waitcnt vmcnt(2)
	ds_write_b128 v183, v[14:17] offset:40960
	s_waitcnt vmcnt(1)
	ds_write_b128 v183, v[18:21] offset:49152
	s_waitcnt vmcnt(0)
	ds_write_b128 v183, v[22:25] offset:57344
	v_add_co_u32_e32 v6, vcc, s77, v28
	s_add_i32 s40, s13, 0x200
	s_nop 0
	v_addc_co_u32_e32 v7, vcc, 0, v29, vcc
	s_cmp_eq_u32 s39, 2
	v_add_co_u32_e32 v14, vcc, s77, v26
	s_cselect_b32 s44, 0, s40
	s_nop 0
	v_addc_co_u32_e32 v15, vcc, 0, v27, vcc
	s_cselect_b32 s40, s23, 0
	s_cselect_b32 s46, s36, 0
	s_sub_i32 s44, s44, s13
	v_add_co_u32_e32 v18, vcc, 0x60000, v26
	s_ashr_i32 s41, s40, 31
	s_ashr_i32 s45, s44, 31
	v_addc_co_u32_e32 v19, vcc, 0, v27, vcc
	v_lshl_add_u64 v[2:3], s[40:41], 1, v[28:29]
	s_lshl_b64 s[40:41], s[44:45], 1
	v_mov_b32_e32 v0, 0xc00
	v_add_co_u32_e32 v22, vcc, 0x90000, v26
	v_lshl_add_u64 v[172:173], v[2:3], 0, s[40:41]
	v_mad_i64_i32 v[2:3], s[44:45], s46, v0, v[26:27]
	v_addc_co_u32_e32 v23, vcc, 0, v27, vcc
	v_lshl_add_u64 v[176:177], v[2:3], 0, s[40:41]
	global_load_dwordx4 v[2:5], v[28:29], off offset:128
	global_load_dwordx4 v[10:13], v[6:7], off offset:128
	s_nop 0
	global_load_dwordx4 v[6:9], v[26:27], off offset:128
	v_mov_b32_e32 v26, 0
	global_load_dwordx4 v[14:17], v[14:15], off offset:128
	s_mov_b32 s12, 0
	global_load_dwordx4 v[18:21], v[18:19], off offset:128
	v_mov_b64_e32 v[178:179], v[132:133]
	global_load_dwordx4 v[22:25], v[22:23], off offset:128
	v_mov_b64_e32 v[180:181], v[128:129]
	v_mov_b32_e32 v27, v26
	v_mov_b32_e32 v28, v26
	v_mov_b32_e32 v29, v26
	v_mov_b32_e32 v30, v26
	v_mov_b32_e32 v31, v26
	v_mov_b32_e32 v32, v26
	v_mov_b32_e32 v33, v26
	v_mov_b32_e32 v34, v26
	v_mov_b32_e32 v35, v26
	v_mov_b32_e32 v36, v26
	v_mov_b32_e32 v37, v26
	v_mov_b32_e32 v38, v26
	v_mov_b32_e32 v39, v26
	v_mov_b32_e32 v40, v26
	v_mov_b32_e32 v41, v26
	v_mov_b32_e32 v42, v26
	v_mov_b32_e32 v43, v26
	v_mov_b32_e32 v44, v26
	v_mov_b32_e32 v45, v26
	v_mov_b32_e32 v46, v26
	v_mov_b32_e32 v47, v26
	v_mov_b32_e32 v48, v26
	v_mov_b32_e32 v49, v26
	v_mov_b32_e32 v50, v26
	v_mov_b32_e32 v51, v26
	v_mov_b32_e32 v52, v26
	v_mov_b32_e32 v53, v26
	v_mov_b32_e32 v54, v26
	v_mov_b32_e32 v55, v26
	v_mov_b32_e32 v56, v26
	v_mov_b32_e32 v57, v26
	v_mov_b32_e32 v58, v26
	v_mov_b32_e32 v59, v26
	v_mov_b32_e32 v60, v26
	v_mov_b32_e32 v61, v26
	v_mov_b32_e32 v62, v26
	v_mov_b32_e32 v63, v26
	v_mov_b32_e32 v64, v26
	v_mov_b32_e32 v65, v26
	v_mov_b32_e32 v66, v26
	v_mov_b32_e32 v67, v26
	v_mov_b32_e32 v68, v26
	v_mov_b32_e32 v69, v26
	v_mov_b32_e32 v70, v26
	v_mov_b32_e32 v71, v26
	v_mov_b32_e32 v72, v26
	v_mov_b32_e32 v73, v26
	v_mov_b32_e32 v74, v26
	v_mov_b32_e32 v75, v26
	v_mov_b32_e32 v76, v26
	v_mov_b32_e32 v77, v26
	v_mov_b32_e32 v78, v26
	v_mov_b32_e32 v79, v26
	v_mov_b32_e32 v80, v26
	v_mov_b32_e32 v81, v26
	v_mov_b32_e32 v82, v26
	v_mov_b32_e32 v83, v26
	v_mov_b32_e32 v84, v26
	v_mov_b32_e32 v85, v26
	v_mov_b32_e32 v86, v26
	v_mov_b32_e32 v87, v26
	v_mov_b32_e32 v88, v26
	v_mov_b32_e32 v89, v26
	s_lshl_b32 s47, s39, 11
	s_add_u32 s48, s37, s47
	s_addc_u32 s49, s38, 0
	s_mul_i32 s47, s22, 0x1800
	s_add_u32 s48, s48, s47
	s_addc_u32 s49, s49, 0
	v_lshrrev_b32_e32 v250, 5, v175
	v_and_b32_e32 v251, 31, v175
	v_mul_u32_u24_e32 v250, 0x1800, v250
	v_lshl_add_u32 v250, v251, 4, v250
	global_load_dwordx4 v[212:215], v250, s[48:49]
	s_add_u32 s50, s48, 0x18000
	s_addc_u32 s51, s49, 0
	global_load_dwordx4 v[216:219], v250, s[50:51]
	s_add_u32 s52, s50, 0x18000
	s_addc_u32 s53, s51, 0
	global_load_dwordx4 v[220:223], v250, s[52:53]
	s_add_u32 s48, s52, 0x18000
	s_addc_u32 s49, s53, 0
	global_load_dwordx4 v[224:227], v250, s[48:49]
	s_add_u32 s50, s48, 0x18000
	s_addc_u32 s51, s49, 0
	global_load_dwordx4 v[234:237], v250, s[50:51]
	s_add_u32 s52, s50, 0x18000
	s_addc_u32 s53, s51, 0
	global_load_dwordx4 v[238:241], v250, s[52:53]
	s_add_u32 s48, s52, 0x18000
	s_addc_u32 s49, s53, 0
	global_load_dwordx4 v[242:245], v250, s[48:49]
	s_add_u32 s50, s48, 0x18000
	s_addc_u32 s51, s49, 0
	global_load_dwordx2 v[228:229], v250, s[50:51]
	global_load_dwordx2 v[250:251], v250, s[50:51] offset:8
	s_waitcnt lgkmcnt(0)
	s_barrier
; template <int MI, int NJ> ...
;     ...
;   for (int kt = 0; kt < nk; ++kt) {
;     const int buf = kt & 1;
;     {
;       G8STORE(buf ^ 1);
;       const u16* ga_ = (kt + 2 < nk) ? Ag + (kt + 2) * 64 : Ag + nAoff;
;       const u16* gb_ = (kt + 2 < nk) ? Bg + (kt + 2) * 64 : Bg + nBoff;
;       G8LOADP(ga_, gb_);
;     }
;     __builtin_amdgcn_sched_barrier(0);
;     __builtin_amdgcn_s_setprio(1);
;     const u16* a = ra_ + buf * AROWS * 64;
;     const u16* b = rb_ + buf * BROWS * 64;
; #pragma unroll
;     for (int ks = 0; ks < 2; ++ks) {
;       const u16* a_ = ks ? a + dsw : a;
;       const u16* b_ = ks ? b + dsw : b;
;       bf16x8 bfr[NJ];
; #pragma unroll
;       for (int j = 0; j < NJ; ++j) bfr[j] = *(const bf16x8*)(b_ + j * 16 * 64);
; #pragma unroll
;       for (int ih = 0; ih < MI / 4; ++ih) {
;         bf16x8 af[4];
; #pragma unroll
;         for (int i = 0; i < 4; ++i) af[i] = *(const bf16x8*)(a_ + (ih * 4 + i) * 16 * 64);
; #pragma unroll
;         for (int i = 0; i < 4; ++i)
; #pragma unroll
;           for (int j = 0; j < NJ; ++j) acc[ih * 4 + i][j] = mfma16(af[i], bfr[j], acc[ih * 4 + i][j]);
;       }
;     }
;     __builtin_amdgcn_s_setprio(0);
;     __builtin_amdgcn_sched_barrier(0);
;     __syncthreads();
; __device__ __forceinline__ void phase_merge(const Params& p, u16* smem, volatile LAS unsigned* vb_) {
;     ...
;       for (int k = 0; k < 8; ++k) {
;         const int c = tid2 + 512 * k;
;         const int row = c >> 5, ch = c & 31;
;         *(uint4*)(smem + row * 264 + ch * 8) = *(const uint4*)(MG + (size_t)(mt * 128 + row) * 3072 + n * 1024 + nt * 256 + ch * 8);
;       }
;       __syncthreads();
.LBB0_26:
	s_and_b32 s13, s12, 1
	s_xor_b32 s40, s13, 1
	s_cmp_lt_u32 s12, 6
	v_lshl_add_u32 v0, s40, 14, v183
	s_cselect_b64 vcc, -1, 0
	v_lshl_add_u32 v187, s40, 15, v183
	s_waitcnt vmcnt(5)
	ds_write_b128 v0, v[2:5]
	s_waitcnt vmcnt(3)
	ds_write_b128 v0, v[10:13] offset:8192
	s_waitcnt vmcnt(3)
	ds_write_b128 v187, v[6:9] offset:32768
	s_waitcnt vmcnt(2)
	ds_write_b128 v187, v[14:17] offset:40960
	s_waitcnt vmcnt(1)
	ds_write_b128 v187, v[18:21] offset:49152
	s_waitcnt vmcnt(0)
	ds_write_b128 v187, v[22:25] offset:57344
	v_cndmask_b32_e32 v6, v172, v178, vcc
	v_cndmask_b32_e32 v7, v173, v179, vcc
	v_cndmask_b32_e32 v11, v177, v181, vcc
	v_cndmask_b32_e32 v10, v176, v180, vcc
	v_add_co_u32_e32 v12, vcc, s77, v6
	s_mov_b32 s40, 0x90000
	s_nop 0
	v_addc_co_u32_e32 v13, vcc, 0, v7, vcc
	v_add_co_u32_e32 v14, vcc, s77, v10
	global_load_dwordx4 v[2:5], v[6:7], off
	s_nop 0
	v_addc_co_u32_e32 v15, vcc, 0, v11, vcc
	v_add_co_u32_e32 v18, vcc, s54, v10
	global_load_dwordx4 v[6:9], v[10:11], off
	s_nop 0
	v_addc_co_u32_e32 v19, vcc, 0, v11, vcc
	v_add_co_u32_e32 v22, vcc, s40, v10
	s_nop 1
	v_addc_co_u32_e32 v23, vcc, 0, v11, vcc
	global_load_dwordx4 v[10:13], v[12:13], off
	s_nop 0
	global_load_dwordx4 v[14:17], v[14:15], off
	s_nop 0
	global_load_dwordx4 v[18:21], v[18:19], off
	s_nop 0
	global_load_dwordx4 v[22:25], v[22:23], off
	s_setprio 1
	v_lshl_add_u32 v0, s13, 14, v184
	v_lshl_or_b32 v187, s13, 15, v185
	ds_read_b128 v[192:195], v187 offset:32768
	ds_read_b128 v[196:199], v187 offset:34816
	ds_read_b128 v[204:207], v187 offset:36864
	ds_read_b128 v[208:211], v187 offset:38912
	ds_read_b128 v[188:191], v0
	ds_read_b128 v[246:249], v0 offset:2048
	v_add_u32_e32 v187, v187, v186
	s_waitcnt lgkmcnt(1)
	v_mfma_f32_16x16x32_bf16 v[86:89], v[188:191], v[192:195], v[86:89]
	s_waitcnt lgkmcnt(4)
	v_mfma_f32_16x16x32_bf16 v[82:85], v[188:191], v[196:199], v[82:85]
	s_waitcnt lgkmcnt(3)
	v_mfma_f32_16x16x32_bf16 v[78:81], v[188:191], v[204:207], v[78:81]
	s_waitcnt lgkmcnt(2)
	v_mfma_f32_16x16x32_bf16 v[74:77], v[188:191], v[208:211], v[74:77]
	ds_read_b128 v[188:191], v0 offset:4096
	s_waitcnt lgkmcnt(1)
	v_mfma_f32_16x16x32_bf16 v[70:73], v[246:249], v[192:195], v[70:73]
	v_mfma_f32_16x16x32_bf16 v[66:69], v[246:249], v[196:199], v[66:69]
	v_mfma_f32_16x16x32_bf16 v[62:65], v[246:249], v[204:207], v[62:65]
	v_mfma_f32_16x16x32_bf16 v[58:61], v[246:249], v[208:211], v[58:61]
	ds_read_b128 v[246:249], v0 offset:6144
	v_add_u32_e32 v0, v0, v186
	s_waitcnt lgkmcnt(1)
	v_mfma_f32_16x16x32_bf16 v[54:57], v[188:191], v[192:195], v[54:57]
	v_mfma_f32_16x16x32_bf16 v[50:53], v[188:191], v[196:199], v[50:53]
	v_mfma_f32_16x16x32_bf16 v[46:49], v[188:191], v[204:207], v[46:49]
	v_mfma_f32_16x16x32_bf16 v[42:45], v[188:191], v[208:211], v[42:45]
	ds_read_b128 v[188:191], v0
	s_waitcnt lgkmcnt(1)
	v_mfma_f32_16x16x32_bf16 v[38:41], v[246:249], v[192:195], v[38:41]
	ds_read_b128 v[192:195], v187 offset:32768
	v_mfma_f32_16x16x32_bf16 v[34:37], v[246:249], v[196:199], v[34:37]
	ds_read_b128 v[196:199], v187 offset:34816
	v_mfma_f32_16x16x32_bf16 v[30:33], v[246:249], v[204:207], v[30:33]
	ds_read_b128 v[204:207], v187 offset:36864
	v_mfma_f32_16x16x32_bf16 v[26:29], v[246:249], v[208:211], v[26:29]
	ds_read_b128 v[208:211], v187 offset:38912
	ds_read_b128 v[246:249], v0 offset:2048
	s_waitcnt lgkmcnt(4)
	v_mfma_f32_16x16x32_bf16 v[86:89], v[188:191], v[192:195], v[86:89]
	s_waitcnt lgkmcnt(3)
	v_mfma_f32_16x16x32_bf16 v[82:85], v[188:191], v[196:199], v[82:85]
	s_waitcnt lgkmcnt(2)
	v_mfma_f32_16x16x32_bf16 v[78:81], v[188:191], v[204:207], v[78:81]
	s_waitcnt lgkmcnt(1)
	v_mfma_f32_16x16x32_bf16 v[74:77], v[188:191], v[208:211], v[74:77]
	ds_read_b128 v[188:191], v0 offset:4096
	s_waitcnt lgkmcnt(1)
	v_mfma_f32_16x16x32_bf16 v[70:73], v[246:249], v[192:195], v[70:73]
	v_mfma_f32_16x16x32_bf16 v[66:69], v[246:249], v[196:199], v[66:69]
	v_mfma_f32_16x16x32_bf16 v[62:65], v[246:249], v[204:207], v[62:65]
	v_mfma_f32_16x16x32_bf16 v[58:61], v[246:249], v[208:211], v[58:61]
	ds_read_b128 v[246:249], v0 offset:6144
	s_waitcnt lgkmcnt(1)
	v_mfma_f32_16x16x32_bf16 v[54:57], v[188:191], v[192:195], v[54:57]
	v_mfma_f32_16x16x32_bf16 v[50:53], v[188:191], v[196:199], v[50:53]
	v_mfma_f32_16x16x32_bf16 v[46:49], v[188:191], v[204:207], v[46:49]
	v_mfma_f32_16x16x32_bf16 v[42:45], v[188:191], v[208:211], v[42:45]
	s_waitcnt lgkmcnt(0)
	v_mfma_f32_16x16x32_bf16 v[38:41], v[246:249], v[192:195], v[38:41]
	v_mfma_f32_16x16x32_bf16 v[34:37], v[246:249], v[196:199], v[34:37]
	v_mfma_f32_16x16x32_bf16 v[30:33], v[246:249], v[204:207], v[30:33]
	v_mfma_f32_16x16x32_bf16 v[26:29], v[246:249], v[208:211], v[26:29]
	s_setprio 0
	s_add_i32 s12, s12, 1
	v_lshl_add_u64 v[180:181], v[180:181], 0, s[26:27]
	s_cmp_lg_u32 s12, 8
	v_lshl_add_u64 v[178:179], v[178:179], 0, s[26:27]
	s_barrier
	s_cbranch_scc1 .LBB0_26
	v_lshrrev_b32_e32 v204, 5, v175
	v_and_b32_e32 v205, 31, v175
	v_mul_u32_u24_e32 v204, 0x210, v204
	v_lshl_add_u32 v204, v205, 4, v204
	s_waitcnt vmcnt(6)
	ds_write_b128 v204, v[212:215]
	ds_write_b128 v204, v[216:219] offset:8448
	ds_write_b128 v204, v[220:223] offset:16896
	ds_write_b128 v204, v[224:227] offset:25344
	ds_write_b128 v204, v[234:237] offset:33792
	ds_write_b128 v204, v[238:241] offset:42240
	ds_write_b128 v204, v[242:245] offset:50688
	ds_write_b64 v204, v[228:229] offset:59136
	ds_write_b64 v204, v[250:251] offset:59144
	s_waitcnt lgkmcnt(0)
	s_barrier
; __device__ __forceinline__ float bf2f(u16 h) { return __uint_as_float(((u32)h) << 16); }
; __device__ __forceinline__ float sigmoidf_(float x) { return 1.0f / (1.0f + __expf(-x)); }
; __device__ __forceinline__ void phase_merge(const Params& p, u16* smem, volatile LAS unsigned* vb_) {
;     ...
; #pragma unroll
;       for (int i = 0; i < 4; ++i)
; #pragma unroll
;         for (int j = 0; j < 4; ++j)
; #pragma unroll
;           for (int r = 0; r < 4; ++r) {
;             const float g = sigmoidf_(bf2f(smem[(wm * 64 + i * 16 + (lane >> 4) * 4 + r) * 264 + wn * 64 + j * 16 + (lane & 15)]));
;             tot[i][j][r] += g * acc[i][j][r];
;             if (r == 3) __builtin_amdgcn_sched_barrier(0);
;           }
	ds_read_u16 v212, v94
	ds_read_u16 v213, v94 offset:528
	ds_read_u16 v214, v94 offset:1056
	ds_read_u16 v215, v94 offset:1584
	ds_read_u16 v216, v94 offset:32
	ds_read_u16 v217, v94 offset:560
	ds_read_u16 v218, v94 offset:1088
	ds_read_u16 v219, v94 offset:1616
	s_waitcnt lgkmcnt(0)
	ds_read_u16 v204, v94 offset:64
	ds_read_u16 v205, v94 offset:592
	ds_read_u16 v206, v94 offset:1120
	ds_read_u16 v207, v94 offset:1648
	ds_read_u16 v208, v94 offset:96
	ds_read_u16 v209, v94 offset:624
	ds_read_u16 v210, v94 offset:1152
	ds_read_u16 v211, v94 offset:1680
	v_lshlrev_b32_e32 v212, 16, v212
	v_lshlrev_b32_e32 v213, 16, v213
	v_lshlrev_b32_e32 v214, 16, v214
	v_lshlrev_b32_e32 v215, 16, v215
	v_lshlrev_b32_e32 v216, 16, v216
	v_lshlrev_b32_e32 v217, 16, v217
	v_lshlrev_b32_e32 v218, 16, v218
	v_lshlrev_b32_e32 v219, 16, v219
	v_mul_f32_e32 v212, 0xbfb8aa3b, v212
	v_mul_f32_e32 v213, 0xbfb8aa3b, v213
	v_mul_f32_e32 v214, 0xbfb8aa3b, v214
	v_mul_f32_e32 v215, 0xbfb8aa3b, v215
	v_mul_f32_e32 v216, 0xbfb8aa3b, v216
	v_mul_f32_e32 v217, 0xbfb8aa3b, v217
	v_mul_f32_e32 v218, 0xbfb8aa3b, v218
	v_mul_f32_e32 v219, 0xbfb8aa3b, v219
	v_min_f32_e32 v212, 0x42fc0000, v212
	v_min_f32_e32 v213, 0x42fc0000, v213
	v_min_f32_e32 v214, 0x42fc0000, v214
	v_min_f32_e32 v215, 0x42fc0000, v215
	v_min_f32_e32 v216, 0x42fc0000, v216
	v_min_f32_e32 v217, 0x42fc0000, v217
	v_min_f32_e32 v218, 0x42fc0000, v218
	v_min_f32_e32 v219, 0x42fc0000, v219
	v_exp_f32_e32 v212, v212
	v_exp_f32_e32 v213, v213
	v_exp_f32_e32 v214, v214
	v_exp_f32_e32 v215, v215
	v_exp_f32_e32 v216, v216
	v_exp_f32_e32 v217, v217
	v_exp_f32_e32 v218, v218
	v_exp_f32_e32 v219, v219
	v_add_f32_e32 v212, 1.0, v212
	v_add_f32_e32 v213, 1.0, v213
	v_add_f32_e32 v214, 1.0, v214
	v_add_f32_e32 v215, 1.0, v215
	v_add_f32_e32 v216, 1.0, v216
	v_add_f32_e32 v217, 1.0, v217
	v_add_f32_e32 v218, 1.0, v218
	v_add_f32_e32 v219, 1.0, v219
	v_rcp_f32_e32 v220, v212
	v_rcp_f32_e32 v221, v213
	v_rcp_f32_e32 v222, v214
	v_rcp_f32_e32 v223, v215
	v_rcp_f32_e32 v224, v216
	v_rcp_f32_e32 v225, v217
	v_rcp_f32_e32 v226, v218
	v_rcp_f32_e32 v227, v219
	v_fma_f32 v212, -v212, v220, 1.0
	v_fma_f32 v213, -v213, v221, 1.0
	v_fma_f32 v214, -v214, v222, 1.0
	v_fma_f32 v215, -v215, v223, 1.0
	v_fma_f32 v216, -v216, v224, 1.0
	v_fma_f32 v217, -v217, v225, 1.0
	v_fma_f32 v218, -v218, v226, 1.0
	v_fma_f32 v219, -v219, v227, 1.0
	v_fmac_f32_e32 v220, v212, v220
	v_fmac_f32_e32 v221, v213, v221
	v_fmac_f32_e32 v222, v214, v222
	v_fmac_f32_e32 v223, v215, v223
	v_fmac_f32_e32 v224, v216, v224
	v_fmac_f32_e32 v225, v217, v225
	v_fmac_f32_e32 v226, v218, v226
	v_fmac_f32_e32 v227, v219, v227
	v_fmac_f32_e32 v170, v86, v220
	v_fmac_f32_e32 v171, v87, v221
	v_fmac_f32_e32 v168, v88, v222
	v_fmac_f32_e32 v169, v89, v223
	v_fmac_f32_e32 v166, v82, v224
	v_fmac_f32_e32 v167, v83, v225
	v_fmac_f32_e32 v164, v84, v226
	v_fmac_f32_e32 v165, v85, v227
	s_waitcnt lgkmcnt(0)
	ds_read_u16 v212, v94 offset:8448
	ds_read_u16 v213, v94 offset:8976
	ds_read_u16 v214, v94 offset:9504
	ds_read_u16 v215, v94 offset:10032
	ds_read_u16 v216, v94 offset:8480
	ds_read_u16 v217, v94 offset:9008
	ds_read_u16 v218, v94 offset:9536
	ds_read_u16 v219, v94 offset:10064
	v_lshlrev_b32_e32 v204, 16, v204
	v_lshlrev_b32_e32 v205, 16, v205
	v_lshlrev_b32_e32 v206, 16, v206
	v_lshlrev_b32_e32 v207, 16, v207
	v_lshlrev_b32_e32 v208, 16, v208
	v_lshlrev_b32_e32 v209, 16, v209
	v_lshlrev_b32_e32 v210, 16, v210
	v_lshlrev_b32_e32 v211, 16, v211
	v_mul_f32_e32 v204, 0xbfb8aa3b, v204
	v_mul_f32_e32 v205, 0xbfb8aa3b, v205
	v_mul_f32_e32 v206, 0xbfb8aa3b, v206
	v_mul_f32_e32 v207, 0xbfb8aa3b, v207
	v_mul_f32_e32 v208, 0xbfb8aa3b, v208
	v_mul_f32_e32 v209, 0xbfb8aa3b, v209
	v_mul_f32_e32 v210, 0xbfb8aa3b, v210
	v_mul_f32_e32 v211, 0xbfb8aa3b, v211
	v_min_f32_e32 v204, 0x42fc0000, v204
	v_min_f32_e32 v205, 0x42fc0000, v205
	v_min_f32_e32 v206, 0x42fc0000, v206
	v_min_f32_e32 v207, 0x42fc0000, v207
	v_min_f32_e32 v208, 0x42fc0000, v208
	v_min_f32_e32 v209, 0x42fc0000, v209
	v_min_f32_e32 v210, 0x42fc0000, v210
	v_min_f32_e32 v211, 0x42fc0000, v211
	v_exp_f32_e32 v204, v204
	v_exp_f32_e32 v205, v205
	v_exp_f32_e32 v206, v206
	v_exp_f32_e32 v207, v207
	v_exp_f32_e32 v208, v208
	v_exp_f32_e32 v209, v209
	v_exp_f32_e32 v210, v210
	v_exp_f32_e32 v211, v211
	v_add_f32_e32 v204, 1.0, v204
	v_add_f32_e32 v205, 1.0, v205
	v_add_f32_e32 v206, 1.0, v206
	v_add_f32_e32 v207, 1.0, v207
	v_add_f32_e32 v208, 1.0, v208
	v_add_f32_e32 v209, 1.0, v209
	v_add_f32_e32 v210, 1.0, v210
	v_add_f32_e32 v211, 1.0, v211
	v_rcp_f32_e32 v220, v204
	v_rcp_f32_e32 v221, v205
	v_rcp_f32_e32 v222, v206
	v_rcp_f32_e32 v223, v207
	v_rcp_f32_e32 v224, v208
	v_rcp_f32_e32 v225, v209
	v_rcp_f32_e32 v226, v210
	v_rcp_f32_e32 v227, v211
	v_fma_f32 v204, -v204, v220, 1.0
	v_fma_f32 v205, -v205, v221, 1.0
	v_fma_f32 v206, -v206, v222, 1.0
	v_fma_f32 v207, -v207, v223, 1.0
	v_fma_f32 v208, -v208, v224, 1.0
	v_fma_f32 v209, -v209, v225, 1.0
	v_fma_f32 v210, -v210, v226, 1.0
	v_fma_f32 v211, -v211, v227, 1.0
	v_fmac_f32_e32 v220, v204, v220
	v_fmac_f32_e32 v221, v205, v221
	v_fmac_f32_e32 v222, v206, v222
	v_fmac_f32_e32 v223, v207, v223
	v_fmac_f32_e32 v224, v208, v224
	v_fmac_f32_e32 v225, v209, v225
	v_fmac_f32_e32 v226, v210, v226
	v_fmac_f32_e32 v227, v211, v227
	v_fmac_f32_e32 v162, v78, v220
	v_fmac_f32_e32 v163, v79, v221
	v_fmac_f32_e32 v160, v80, v222
	v_fmac_f32_e32 v161, v81, v223
	v_fmac_f32_e32 v158, v74, v224
	v_fmac_f32_e32 v159, v75, v225
	v_fmac_f32_e32 v156, v76, v226
	v_fmac_f32_e32 v157, v77, v227
	s_waitcnt lgkmcnt(0)
; __device__ __forceinline__ float bf2f(u16 h) { return __uint_as_float(((u32)h) << 16); }
; __device__ __forceinline__ float sigmoidf_(float x) { return 1.0f / (1.0f + __expf(-x)); }
; __device__ __forceinline__ void phase_merge(const Params& p, u16* smem, volatile LAS unsigned* vb_) {
;     ...
; #pragma unroll
;       for (int i = 0; i < 4; ++i)
; #pragma unroll
;         for (int j = 0; j < 4; ++j)
; #pragma unroll
;           for (int r = 0; r < 4; ++r) {
;             const float g = sigmoidf_(bf2f(smem[(wm * 64 + i * 16 + (lane >> 4) * 4 + r) * 264 + wn * 64 + j * 16 + (lane & 15)]));
;             tot[i][j][r] += g * acc[i][j][r];
;             if (r == 3) __builtin_amdgcn_sched_barrier(0);
;           }
	ds_read_u16 v204, v94 offset:8512
	ds_read_u16 v205, v94 offset:9040
	ds_read_u16 v206, v94 offset:9568
	ds_read_u16 v207, v94 offset:10096
	ds_read_u16 v208, v94 offset:8544
	ds_read_u16 v209, v94 offset:9072
	ds_read_u16 v210, v94 offset:9600
	ds_read_u16 v211, v94 offset:10128
	v_lshlrev_b32_e32 v212, 16, v212
	v_lshlrev_b32_e32 v213, 16, v213
	v_lshlrev_b32_e32 v214, 16, v214
	v_lshlrev_b32_e32 v215, 16, v215
	v_lshlrev_b32_e32 v216, 16, v216
	v_lshlrev_b32_e32 v217, 16, v217
	v_lshlrev_b32_e32 v218, 16, v218
	v_lshlrev_b32_e32 v219, 16, v219
	v_mul_f32_e32 v212, 0xbfb8aa3b, v212
	v_mul_f32_e32 v213, 0xbfb8aa3b, v213
	v_mul_f32_e32 v214, 0xbfb8aa3b, v214
	v_mul_f32_e32 v215, 0xbfb8aa3b, v215
	v_mul_f32_e32 v216, 0xbfb8aa3b, v216
	v_mul_f32_e32 v217, 0xbfb8aa3b, v217
	v_mul_f32_e32 v218, 0xbfb8aa3b, v218
	v_mul_f32_e32 v219, 0xbfb8aa3b, v219
	v_min_f32_e32 v212, 0x42fc0000, v212
	v_min_f32_e32 v213, 0x42fc0000, v213
	v_min_f32_e32 v214, 0x42fc0000, v214
	v_min_f32_e32 v215, 0x42fc0000, v215
	v_min_f32_e32 v216, 0x42fc0000, v216
	v_min_f32_e32 v217, 0x42fc0000, v217
	v_min_f32_e32 v218, 0x42fc0000, v218
	v_min_f32_e32 v219, 0x42fc0000, v219
	v_exp_f32_e32 v212, v212
	v_exp_f32_e32 v213, v213
	v_exp_f32_e32 v214, v214
	v_exp_f32_e32 v215, v215
	v_exp_f32_e32 v216, v216
	v_exp_f32_e32 v217, v217
	v_exp_f32_e32 v218, v218
	v_exp_f32_e32 v219, v219
	v_add_f32_e32 v212, 1.0, v212
	v_add_f32_e32 v213, 1.0, v213
	v_add_f32_e32 v214, 1.0, v214
	v_add_f32_e32 v215, 1.0, v215
	v_add_f32_e32 v216, 1.0, v216
	v_add_f32_e32 v217, 1.0, v217
	v_add_f32_e32 v218, 1.0, v218
	v_add_f32_e32 v219, 1.0, v219
	v_rcp_f32_e32 v220, v212
	v_rcp_f32_e32 v221, v213
	v_rcp_f32_e32 v222, v214
	v_rcp_f32_e32 v223, v215
	v_rcp_f32_e32 v224, v216
	v_rcp_f32_e32 v225, v217
	v_rcp_f32_e32 v226, v218
	v_rcp_f32_e32 v227, v219
	v_fma_f32 v212, -v212, v220, 1.0
	v_fma_f32 v213, -v213, v221, 1.0
	v_fma_f32 v214, -v214, v222, 1.0
	v_fma_f32 v215, -v215, v223, 1.0
	v_fma_f32 v216, -v216, v224, 1.0
	v_fma_f32 v217, -v217, v225, 1.0
	v_fma_f32 v218, -v218, v226, 1.0
	v_fma_f32 v219, -v219, v227, 1.0
	v_fmac_f32_e32 v220, v212, v220
	v_fmac_f32_e32 v221, v213, v221
	v_fmac_f32_e32 v222, v214, v222
	v_fmac_f32_e32 v223, v215, v223
	v_fmac_f32_e32 v224, v216, v224
	v_fmac_f32_e32 v225, v217, v225
	v_fmac_f32_e32 v226, v218, v226
	v_fmac_f32_e32 v227, v219, v227
	v_fmac_f32_e32 v154, v70, v220
	v_fmac_f32_e32 v155, v71, v221
	v_fmac_f32_e32 v152, v72, v222
	v_fmac_f32_e32 v153, v73, v223
	v_fmac_f32_e32 v150, v66, v224
	v_fmac_f32_e32 v151, v67, v225
	v_fmac_f32_e32 v148, v68, v226
	v_fmac_f32_e32 v149, v69, v227
	s_waitcnt lgkmcnt(0)
	ds_read_u16 v212, v94 offset:16896
	ds_read_u16 v213, v94 offset:17424
	ds_read_u16 v214, v94 offset:17952
	ds_read_u16 v215, v94 offset:18480
	ds_read_u16 v216, v94 offset:16928
	ds_read_u16 v217, v94 offset:17456
	ds_read_u16 v218, v94 offset:17984
	ds_read_u16 v219, v94 offset:18512
	v_lshlrev_b32_e32 v204, 16, v204
	v_lshlrev_b32_e32 v205, 16, v205
	v_lshlrev_b32_e32 v206, 16, v206
	v_lshlrev_b32_e32 v207, 16, v207
	v_lshlrev_b32_e32 v208, 16, v208
	v_lshlrev_b32_e32 v209, 16, v209
	v_lshlrev_b32_e32 v210, 16, v210
	v_lshlrev_b32_e32 v211, 16, v211
	v_mul_f32_e32 v204, 0xbfb8aa3b, v204
	v_mul_f32_e32 v205, 0xbfb8aa3b, v205
	v_mul_f32_e32 v206, 0xbfb8aa3b, v206
	v_mul_f32_e32 v207, 0xbfb8aa3b, v207
	v_mul_f32_e32 v208, 0xbfb8aa3b, v208
	v_mul_f32_e32 v209, 0xbfb8aa3b, v209
	v_mul_f32_e32 v210, 0xbfb8aa3b, v210
	v_mul_f32_e32 v211, 0xbfb8aa3b, v211
	v_min_f32_e32 v204, 0x42fc0000, v204
	v_min_f32_e32 v205, 0x42fc0000, v205
	v_min_f32_e32 v206, 0x42fc0000, v206
	v_min_f32_e32 v207, 0x42fc0000, v207
	v_min_f32_e32 v208, 0x42fc0000, v208
	v_min_f32_e32 v209, 0x42fc0000, v209
	v_min_f32_e32 v210, 0x42fc0000, v210
	v_min_f32_e32 v211, 0x42fc0000, v211
	v_exp_f32_e32 v204, v204
	v_exp_f32_e32 v205, v205
	v_exp_f32_e32 v206, v206
	v_exp_f32_e32 v207, v207
	v_exp_f32_e32 v208, v208
	v_exp_f32_e32 v209, v209
	v_exp_f32_e32 v210, v210
	v_exp_f32_e32 v211, v211
	v_add_f32_e32 v204, 1.0, v204
	v_add_f32_e32 v205, 1.0, v205
	v_add_f32_e32 v206, 1.0, v206
	v_add_f32_e32 v207, 1.0, v207
	v_add_f32_e32 v208, 1.0, v208
	v_add_f32_e32 v209, 1.0, v209
	v_add_f32_e32 v210, 1.0, v210
	v_add_f32_e32 v211, 1.0, v211
	v_rcp_f32_e32 v220, v204
	v_rcp_f32_e32 v221, v205
	v_rcp_f32_e32 v222, v206
	v_rcp_f32_e32 v223, v207
	v_rcp_f32_e32 v224, v208
	v_rcp_f32_e32 v225, v209
	v_rcp_f32_e32 v226, v210
	v_rcp_f32_e32 v227, v211
	v_fma_f32 v204, -v204, v220, 1.0
	v_fma_f32 v205, -v205, v221, 1.0
	v_fma_f32 v206, -v206, v222, 1.0
	v_fma_f32 v207, -v207, v223, 1.0
	v_fma_f32 v208, -v208, v224, 1.0
	v_fma_f32 v209, -v209, v225, 1.0
	v_fma_f32 v210, -v210, v226, 1.0
	v_fma_f32 v211, -v211, v227, 1.0
	v_fmac_f32_e32 v220, v204, v220
	v_fmac_f32_e32 v221, v205, v221
	v_fmac_f32_e32 v222, v206, v222
	v_fmac_f32_e32 v223, v207, v223
	v_fmac_f32_e32 v224, v208, v224
	v_fmac_f32_e32 v225, v209, v225
	v_fmac_f32_e32 v226, v210, v226
	v_fmac_f32_e32 v227, v211, v227
	v_fmac_f32_e32 v146, v62, v220
	v_fmac_f32_e32 v147, v63, v221
	v_fmac_f32_e32 v144, v64, v222
	v_fmac_f32_e32 v145, v65, v223
	v_fmac_f32_e32 v138, v58, v224
	v_fmac_f32_e32 v139, v59, v225
	v_fmac_f32_e32 v136, v60, v226
	v_fmac_f32_e32 v137, v61, v227
	s_waitcnt lgkmcnt(0)
; __device__ __forceinline__ float bf2f(u16 h) { return __uint_as_float(((u32)h) << 16); }
; __device__ __forceinline__ float sigmoidf_(float x) { return 1.0f / (1.0f + __expf(-x)); }
; __device__ __forceinline__ void phase_merge(const Params& p, u16* smem, volatile LAS unsigned* vb_) {
;     ...
; #pragma unroll
;       for (int i = 0; i < 4; ++i)
; #pragma unroll
;         for (int j = 0; j < 4; ++j)
; #pragma unroll
;           for (int r = 0; r < 4; ++r) {
;             const float g = sigmoidf_(bf2f(smem[(wm * 64 + i * 16 + (lane >> 4) * 4 + r) * 264 + wn * 64 + j * 16 + (lane & 15)]));
;             tot[i][j][r] += g * acc[i][j][r];
;             if (r == 3) __builtin_amdgcn_sched_barrier(0);
;           }
	ds_read_u16 v204, v94 offset:16960
	ds_read_u16 v205, v94 offset:17488
	ds_read_u16 v206, v94 offset:18016
	ds_read_u16 v207, v94 offset:18544
	ds_read_u16 v208, v94 offset:16992
	ds_read_u16 v209, v94 offset:17520
	ds_read_u16 v210, v94 offset:18048
	ds_read_u16 v211, v94 offset:18576
	v_lshlrev_b32_e32 v212, 16, v212
	v_lshlrev_b32_e32 v213, 16, v213
	v_lshlrev_b32_e32 v214, 16, v214
	v_lshlrev_b32_e32 v215, 16, v215
	v_lshlrev_b32_e32 v216, 16, v216
	v_lshlrev_b32_e32 v217, 16, v217
	v_lshlrev_b32_e32 v218, 16, v218
	v_lshlrev_b32_e32 v219, 16, v219
	v_mul_f32_e32 v212, 0xbfb8aa3b, v212
	v_mul_f32_e32 v213, 0xbfb8aa3b, v213
	v_mul_f32_e32 v214, 0xbfb8aa3b, v214
	v_mul_f32_e32 v215, 0xbfb8aa3b, v215
	v_mul_f32_e32 v216, 0xbfb8aa3b, v216
	v_mul_f32_e32 v217, 0xbfb8aa3b, v217
	v_mul_f32_e32 v218, 0xbfb8aa3b, v218
	v_mul_f32_e32 v219, 0xbfb8aa3b, v219
	v_min_f32_e32 v212, 0x42fc0000, v212
	v_min_f32_e32 v213, 0x42fc0000, v213
	v_min_f32_e32 v214, 0x42fc0000, v214
	v_min_f32_e32 v215, 0x42fc0000, v215
	v_min_f32_e32 v216, 0x42fc0000, v216
	v_min_f32_e32 v217, 0x42fc0000, v217
	v_min_f32_e32 v218, 0x42fc0000, v218
	v_min_f32_e32 v219, 0x42fc0000, v219
	v_exp_f32_e32 v212, v212
	v_exp_f32_e32 v213, v213
	v_exp_f32_e32 v214, v214
	v_exp_f32_e32 v215, v215
	v_exp_f32_e32 v216, v216
	v_exp_f32_e32 v217, v217
	v_exp_f32_e32 v218, v218
	v_exp_f32_e32 v219, v219
	v_add_f32_e32 v212, 1.0, v212
	v_add_f32_e32 v213, 1.0, v213
	v_add_f32_e32 v214, 1.0, v214
	v_add_f32_e32 v215, 1.0, v215
	v_add_f32_e32 v216, 1.0, v216
	v_add_f32_e32 v217, 1.0, v217
	v_add_f32_e32 v218, 1.0, v218
	v_add_f32_e32 v219, 1.0, v219
	v_rcp_f32_e32 v220, v212
	v_rcp_f32_e32 v221, v213
	v_rcp_f32_e32 v222, v214
	v_rcp_f32_e32 v223, v215
	v_rcp_f32_e32 v224, v216
	v_rcp_f32_e32 v225, v217
	v_rcp_f32_e32 v226, v218
	v_rcp_f32_e32 v227, v219
	v_fma_f32 v212, -v212, v220, 1.0
	v_fma_f32 v213, -v213, v221, 1.0
	v_fma_f32 v214, -v214, v222, 1.0
	v_fma_f32 v215, -v215, v223, 1.0
	v_fma_f32 v216, -v216, v224, 1.0
	v_fma_f32 v217, -v217, v225, 1.0
	v_fma_f32 v218, -v218, v226, 1.0
	v_fma_f32 v219, -v219, v227, 1.0
	v_fmac_f32_e32 v220, v212, v220
	v_fmac_f32_e32 v221, v213, v221
	v_fmac_f32_e32 v222, v214, v222
	v_fmac_f32_e32 v223, v215, v223
	v_fmac_f32_e32 v224, v216, v224
	v_fmac_f32_e32 v225, v217, v225
	v_fmac_f32_e32 v226, v218, v226
	v_fmac_f32_e32 v227, v219, v227
	v_fmac_f32_e32 v134, v54, v220
	v_fmac_f32_e32 v135, v55, v221
	v_fmac_f32_e32 v130, v56, v222
	v_fmac_f32_e32 v131, v57, v223
	v_fmac_f32_e32 v126, v50, v224
	v_fmac_f32_e32 v127, v51, v225
	v_fmac_f32_e32 v124, v52, v226
	v_fmac_f32_e32 v125, v53, v227
	s_waitcnt lgkmcnt(0)
	ds_read_u16 v212, v94 offset:25344
	ds_read_u16 v213, v94 offset:25872
	ds_read_u16 v214, v94 offset:26400
	ds_read_u16 v215, v94 offset:26928
	ds_read_u16 v216, v94 offset:25376
	ds_read_u16 v217, v94 offset:25904
	ds_read_u16 v218, v94 offset:26432
	ds_read_u16 v219, v94 offset:26960
	v_lshlrev_b32_e32 v204, 16, v204
	v_lshlrev_b32_e32 v205, 16, v205
	v_lshlrev_b32_e32 v206, 16, v206
	v_lshlrev_b32_e32 v207, 16, v207
	v_lshlrev_b32_e32 v208, 16, v208
	v_lshlrev_b32_e32 v209, 16, v209
	v_lshlrev_b32_e32 v210, 16, v210
	v_lshlrev_b32_e32 v211, 16, v211
	v_mul_f32_e32 v204, 0xbfb8aa3b, v204
	v_mul_f32_e32 v205, 0xbfb8aa3b, v205
	v_mul_f32_e32 v206, 0xbfb8aa3b, v206
	v_mul_f32_e32 v207, 0xbfb8aa3b, v207
	v_mul_f32_e32 v208, 0xbfb8aa3b, v208
	v_mul_f32_e32 v209, 0xbfb8aa3b, v209
	v_mul_f32_e32 v210, 0xbfb8aa3b, v210
	v_mul_f32_e32 v211, 0xbfb8aa3b, v211
	v_min_f32_e32 v204, 0x42fc0000, v204
	v_min_f32_e32 v205, 0x42fc0000, v205
	v_min_f32_e32 v206, 0x42fc0000, v206
	v_min_f32_e32 v207, 0x42fc0000, v207
	v_min_f32_e32 v208, 0x42fc0000, v208
	v_min_f32_e32 v209, 0x42fc0000, v209
	v_min_f32_e32 v210, 0x42fc0000, v210
	v_min_f32_e32 v211, 0x42fc0000, v211
	v_exp_f32_e32 v204, v204
	v_exp_f32_e32 v205, v205
	v_exp_f32_e32 v206, v206
	v_exp_f32_e32 v207, v207
	v_exp_f32_e32 v208, v208
	v_exp_f32_e32 v209, v209
	v_exp_f32_e32 v210, v210
	v_exp_f32_e32 v211, v211
	v_add_f32_e32 v204, 1.0, v204
	v_add_f32_e32 v205, 1.0, v205
	v_add_f32_e32 v206, 1.0, v206
	v_add_f32_e32 v207, 1.0, v207
	v_add_f32_e32 v208, 1.0, v208
	v_add_f32_e32 v209, 1.0, v209
	v_add_f32_e32 v210, 1.0, v210
	v_add_f32_e32 v211, 1.0, v211
	v_rcp_f32_e32 v220, v204
	v_rcp_f32_e32 v221, v205
	v_rcp_f32_e32 v222, v206
	v_rcp_f32_e32 v223, v207
	v_rcp_f32_e32 v224, v208
	v_rcp_f32_e32 v225, v209
	v_rcp_f32_e32 v226, v210
	v_rcp_f32_e32 v227, v211
	v_fma_f32 v204, -v204, v220, 1.0
	v_fma_f32 v205, -v205, v221, 1.0
	v_fma_f32 v206, -v206, v222, 1.0
	v_fma_f32 v207, -v207, v223, 1.0
	v_fma_f32 v208, -v208, v224, 1.0
	v_fma_f32 v209, -v209, v225, 1.0
	v_fma_f32 v210, -v210, v226, 1.0
	v_fma_f32 v211, -v211, v227, 1.0
	v_fmac_f32_e32 v220, v204, v220
	v_fmac_f32_e32 v221, v205, v221
	v_fmac_f32_e32 v222, v206, v222
	v_fmac_f32_e32 v223, v207, v223
	v_fmac_f32_e32 v224, v208, v224
	v_fmac_f32_e32 v225, v209, v225
	v_fmac_f32_e32 v226, v210, v226
	v_fmac_f32_e32 v227, v211, v227
	v_fmac_f32_e32 v122, v46, v220
	v_fmac_f32_e32 v123, v47, v221
	v_fmac_f32_e32 v120, v48, v222
	v_fmac_f32_e32 v121, v49, v223
	v_fmac_f32_e32 v118, v42, v224
	v_fmac_f32_e32 v119, v43, v225
	v_fmac_f32_e32 v116, v44, v226
	v_fmac_f32_e32 v117, v45, v227
	s_waitcnt lgkmcnt(0)
; #define RTID opaque_tid()
; __device__ __forceinline__ float bf2f(u16 h) { return __uint_as_float(((u32)h) << 16); }
; __device__ __forceinline__ float sigmoidf_(float x) { return 1.0f / (1.0f + __expf(-x)); }
; #define ZERO_ACC(acc)                                  \
;   _Pragma("unroll") for (int i_ = 0; i_ < 4; ++i_)     \
;   _Pragma("unroll") for (int j_ = 0; j_ < 4; ++j_) { acc[i_][j_] = (f32x4){0.f, 0.f, 0.f, 0.f}; }
; __device__ __forceinline__ void phase_merge(const Params& p, u16* smem, volatile LAS unsigned* vb_) {
;     ...
;     for (int n = 0; n < 3; ++n) {
;       f32x4 acc[4][4];
;       ZERO_ACC(acc);
;       gemm8<4, 4>(acc, G8REGS_ARGS, pre, Y, 1536, W, 1536, n * 512, n * 512 + 512, mt * 128, nt * 256,
;                   (n < 2) ? mt * 128 : nmt * 128, (n < 2) ? nt * 256 : nnt * 256, (n < 2) ? (n + 1) * 512 : 0, smem, tid);
;       pre = true;
;       const int tid2 = RTID;
; #pragma unroll
;       for (int k = 0; k < 8; ++k) {
;         const int c = tid2 + 512 * k;
;         const int row = c >> 5, ch = c & 31;
;         *(uint4*)(smem + row * 264 + ch * 8) = *(const uint4*)(MG + (size_t)(mt * 128 + row) * 3072 + n * 1024 + nt * 256 + ch * 8);
;       }
;       __syncthreads();
; #pragma unroll
;       for (int i = 0; i < 4; ++i)
; #pragma unroll
;         for (int j = 0; j < 4; ++j)
; #pragma unroll
;           for (int r = 0; r < 4; ++r) {
;             const float g = sigmoidf_(bf2f(smem[(wm * 64 + i * 16 + (lane >> 4) * 4 + r) * 264 + wn * 64 + j * 16 + (lane & 15)]));
;             tot[i][j][r] += g * acc[i][j][r];
;             if (r == 3) __builtin_amdgcn_sched_barrier(0);
;           }
;       __syncthreads();
;     }
	ds_read_u16 v204, v94 offset:25408
	ds_read_u16 v205, v94 offset:25936
	ds_read_u16 v206, v94 offset:26464
	ds_read_u16 v207, v94 offset:26992
	ds_read_u16 v208, v94 offset:25440
	ds_read_u16 v209, v94 offset:25968
	ds_read_u16 v210, v94 offset:26496
	ds_read_u16 v211, v94 offset:27024
	v_lshlrev_b32_e32 v212, 16, v212
	v_lshlrev_b32_e32 v213, 16, v213
	v_lshlrev_b32_e32 v214, 16, v214
	v_lshlrev_b32_e32 v215, 16, v215
	v_lshlrev_b32_e32 v216, 16, v216
	v_lshlrev_b32_e32 v217, 16, v217
	v_lshlrev_b32_e32 v218, 16, v218
	v_lshlrev_b32_e32 v219, 16, v219
	v_mul_f32_e32 v212, 0xbfb8aa3b, v212
	v_mul_f32_e32 v213, 0xbfb8aa3b, v213
	v_mul_f32_e32 v214, 0xbfb8aa3b, v214
	v_mul_f32_e32 v215, 0xbfb8aa3b, v215
	v_mul_f32_e32 v216, 0xbfb8aa3b, v216
	v_mul_f32_e32 v217, 0xbfb8aa3b, v217
	v_mul_f32_e32 v218, 0xbfb8aa3b, v218
	v_mul_f32_e32 v219, 0xbfb8aa3b, v219
	v_min_f32_e32 v212, 0x42fc0000, v212
	v_min_f32_e32 v213, 0x42fc0000, v213
	v_min_f32_e32 v214, 0x42fc0000, v214
	v_min_f32_e32 v215, 0x42fc0000, v215
	v_min_f32_e32 v216, 0x42fc0000, v216
	v_min_f32_e32 v217, 0x42fc0000, v217
	v_min_f32_e32 v218, 0x42fc0000, v218
	v_min_f32_e32 v219, 0x42fc0000, v219
	v_exp_f32_e32 v212, v212
	v_exp_f32_e32 v213, v213
	v_exp_f32_e32 v214, v214
	v_exp_f32_e32 v215, v215
	v_exp_f32_e32 v216, v216
	v_exp_f32_e32 v217, v217
	v_exp_f32_e32 v218, v218
	v_exp_f32_e32 v219, v219
	v_add_f32_e32 v212, 1.0, v212
	v_add_f32_e32 v213, 1.0, v213
	v_add_f32_e32 v214, 1.0, v214
	v_add_f32_e32 v215, 1.0, v215
	v_add_f32_e32 v216, 1.0, v216
	v_add_f32_e32 v217, 1.0, v217
	v_add_f32_e32 v218, 1.0, v218
	v_add_f32_e32 v219, 1.0, v219
	v_rcp_f32_e32 v220, v212
	v_rcp_f32_e32 v221, v213
	v_rcp_f32_e32 v222, v214
	v_rcp_f32_e32 v223, v215
	v_rcp_f32_e32 v224, v216
	v_rcp_f32_e32 v225, v217
	v_rcp_f32_e32 v226, v218
	v_rcp_f32_e32 v227, v219
	v_fma_f32 v212, -v212, v220, 1.0
	v_fma_f32 v213, -v213, v221, 1.0
	v_fma_f32 v214, -v214, v222, 1.0
	v_fma_f32 v215, -v215, v223, 1.0
	v_fma_f32 v216, -v216, v224, 1.0
	v_fma_f32 v217, -v217, v225, 1.0
	v_fma_f32 v218, -v218, v226, 1.0
	v_fma_f32 v219, -v219, v227, 1.0
	v_fmac_f32_e32 v220, v212, v220
	v_fmac_f32_e32 v221, v213, v221
	v_fmac_f32_e32 v222, v214, v222
	v_fmac_f32_e32 v223, v215, v223
	v_fmac_f32_e32 v224, v216, v224
	v_fmac_f32_e32 v225, v217, v225
	v_fmac_f32_e32 v226, v218, v226
	v_fmac_f32_e32 v227, v219, v227
	v_fmac_f32_e32 v114, v38, v220
	v_fmac_f32_e32 v115, v39, v221
	v_fmac_f32_e32 v112, v40, v222
	v_fmac_f32_e32 v113, v41, v223
	v_fmac_f32_e32 v110, v34, v224
	v_fmac_f32_e32 v111, v35, v225
	v_fmac_f32_e32 v108, v36, v226
	v_fmac_f32_e32 v109, v37, v227
	s_waitcnt lgkmcnt(0)
	v_lshlrev_b32_e32 v204, 16, v204
	v_lshlrev_b32_e32 v205, 16, v205
	v_lshlrev_b32_e32 v206, 16, v206
	v_lshlrev_b32_e32 v207, 16, v207
	v_lshlrev_b32_e32 v208, 16, v208
	v_lshlrev_b32_e32 v209, 16, v209
	v_lshlrev_b32_e32 v210, 16, v210
	v_lshlrev_b32_e32 v211, 16, v211
	v_mul_f32_e32 v204, 0xbfb8aa3b, v204
	v_mul_f32_e32 v205, 0xbfb8aa3b, v205
	v_mul_f32_e32 v206, 0xbfb8aa3b, v206
	v_mul_f32_e32 v207, 0xbfb8aa3b, v207
	v_mul_f32_e32 v208, 0xbfb8aa3b, v208
	v_mul_f32_e32 v209, 0xbfb8aa3b, v209
	v_mul_f32_e32 v210, 0xbfb8aa3b, v210
	v_mul_f32_e32 v211, 0xbfb8aa3b, v211
	v_min_f32_e32 v204, 0x42fc0000, v204
	v_min_f32_e32 v205, 0x42fc0000, v205
	v_min_f32_e32 v206, 0x42fc0000, v206
	v_min_f32_e32 v207, 0x42fc0000, v207
	v_min_f32_e32 v208, 0x42fc0000, v208
	v_min_f32_e32 v209, 0x42fc0000, v209
	v_min_f32_e32 v210, 0x42fc0000, v210
	v_min_f32_e32 v211, 0x42fc0000, v211
	v_exp_f32_e32 v204, v204
	v_exp_f32_e32 v205, v205
	v_exp_f32_e32 v206, v206
	v_exp_f32_e32 v207, v207
	v_exp_f32_e32 v208, v208
	v_exp_f32_e32 v209, v209
	v_exp_f32_e32 v210, v210
	v_exp_f32_e32 v211, v211
	v_add_f32_e32 v204, 1.0, v204
	v_add_f32_e32 v205, 1.0, v205
	v_add_f32_e32 v206, 1.0, v206
	v_add_f32_e32 v207, 1.0, v207
	v_add_f32_e32 v208, 1.0, v208
	v_add_f32_e32 v209, 1.0, v209
	v_add_f32_e32 v210, 1.0, v210
	v_add_f32_e32 v211, 1.0, v211
	v_rcp_f32_e32 v220, v204
	v_rcp_f32_e32 v221, v205
	v_rcp_f32_e32 v222, v206
	v_rcp_f32_e32 v223, v207
	v_rcp_f32_e32 v224, v208
	v_rcp_f32_e32 v225, v209
	v_rcp_f32_e32 v226, v210
	v_rcp_f32_e32 v227, v211
	v_fma_f32 v204, -v204, v220, 1.0
	v_fma_f32 v205, -v205, v221, 1.0
	v_fma_f32 v206, -v206, v222, 1.0
	v_fma_f32 v207, -v207, v223, 1.0
	v_fma_f32 v208, -v208, v224, 1.0
	v_fma_f32 v209, -v209, v225, 1.0
	v_fma_f32 v210, -v210, v226, 1.0
	v_fma_f32 v211, -v211, v227, 1.0
	v_fmac_f32_e32 v220, v204, v220
	v_fmac_f32_e32 v221, v205, v221
	v_fmac_f32_e32 v222, v206, v222
	v_fmac_f32_e32 v223, v207, v223
	v_fmac_f32_e32 v224, v208, v224
	v_fmac_f32_e32 v225, v209, v225
	v_fmac_f32_e32 v226, v210, v226
	v_fmac_f32_e32 v227, v211, v227
	v_fmac_f32_e32 v106, v30, v220
	v_fmac_f32_e32 v107, v31, v221
	v_fmac_f32_e32 v104, v32, v222
	v_fmac_f32_e32 v105, v33, v223
	v_fmac_f32_e32 v100, v26, v224
	v_fmac_f32_e32 v101, v27, v225
	v_fmac_f32_e32 v102, v28, v226
	v_fmac_f32_e32 v103, v29, v227
	s_add_i32 s39, s39, 1
	v_lshl_add_u64 v[128:129], v[128:129], 0, s[18:19]
	v_lshl_add_u64 v[132:133], v[132:133], 0, s[18:19]
	s_cmp_eq_u32 s39, 3
	s_mov_b64 s[12:13], -1
	s_barrier
	s_cbranch_scc0 .LBB0_23
; __device__ __forceinline__ void phase_merge(const Params& p, u16* smem, volatile LAS unsigned* vb_) {
;     ...
; #pragma unroll
;     for (int i = 0; i < 4; ++i)
; #pragma unroll
;       for (int j = 0; j < 4; ++j)
; #pragma unroll
;         for (int r = 0; r < 4; ++r)
;           smem[(wm * 64 + i * 16 + (lane >> 4) * 4 + r) * 264 + wn * 64 + j * 16 + (lane & 15)] = f2bf(tot[i][j][r]);
;     __syncthreads();
	v_cvt_pk_bf16_f32 v0, v170, s0
	ds_write_b16 v94, v0
	v_cvt_pk_bf16_f32 v0, v171, s0
	ds_write_b16 v94, v0 offset:528
	v_cvt_pk_bf16_f32 v0, v168, s0
	ds_write_b16 v94, v0 offset:1056
	v_cvt_pk_bf16_f32 v0, v169, s0
	ds_write_b16 v94, v0 offset:1584
	v_cvt_pk_bf16_f32 v0, v166, s0
	ds_write_b16 v94, v0 offset:32
	v_cvt_pk_bf16_f32 v0, v167, s0
	ds_write_b16 v94, v0 offset:560
	v_cvt_pk_bf16_f32 v0, v164, s0
	ds_write_b16 v94, v0 offset:1088
	v_cvt_pk_bf16_f32 v0, v165, s0
	ds_write_b16 v94, v0 offset:1616
	v_cvt_pk_bf16_f32 v0, v162, s0
	ds_write_b16 v94, v0 offset:64
	v_cvt_pk_bf16_f32 v0, v163, s0
	ds_write_b16 v94, v0 offset:592
	v_cvt_pk_bf16_f32 v0, v160, s0
	ds_write_b16 v94, v0 offset:1120
	v_cvt_pk_bf16_f32 v0, v161, s0
	ds_write_b16 v94, v0 offset:1648
	v_cvt_pk_bf16_f32 v0, v158, s0
	ds_write_b16 v94, v0 offset:96
	v_cvt_pk_bf16_f32 v0, v159, s0
	ds_write_b16 v94, v0 offset:624
	v_cvt_pk_bf16_f32 v0, v156, s0
	ds_write_b16 v94, v0 offset:1152
	v_cvt_pk_bf16_f32 v0, v157, s0
	ds_write_b16 v94, v0 offset:1680
	v_cvt_pk_bf16_f32 v0, v154, s0
	ds_write_b16 v94, v0 offset:8448
	v_cvt_pk_bf16_f32 v0, v155, s0
	ds_write_b16 v94, v0 offset:8976
	v_cvt_pk_bf16_f32 v0, v152, s0
	ds_write_b16 v94, v0 offset:9504
	v_cvt_pk_bf16_f32 v0, v153, s0
	ds_write_b16 v94, v0 offset:10032
	v_cvt_pk_bf16_f32 v0, v150, s0
	ds_write_b16 v94, v0 offset:8480
	v_cvt_pk_bf16_f32 v0, v151, s0
	ds_write_b16 v94, v0 offset:9008
	v_cvt_pk_bf16_f32 v0, v148, s0
	ds_write_b16 v94, v0 offset:9536
	v_cvt_pk_bf16_f32 v0, v149, s0
	ds_write_b16 v94, v0 offset:10064
	v_cvt_pk_bf16_f32 v0, v146, s0
	ds_write_b16 v94, v0 offset:8512
	v_cvt_pk_bf16_f32 v0, v147, s0
	ds_write_b16 v94, v0 offset:9040
	v_cvt_pk_bf16_f32 v0, v144, s0
	ds_write_b16 v94, v0 offset:9568
	v_cvt_pk_bf16_f32 v0, v145, s0
	ds_write_b16 v94, v0 offset:10096
	v_cvt_pk_bf16_f32 v0, v138, s0
	ds_write_b16 v94, v0 offset:8544
	v_cvt_pk_bf16_f32 v0, v139, s0
	ds_write_b16 v94, v0 offset:9072
	v_cvt_pk_bf16_f32 v0, v136, s0
	ds_write_b16 v94, v0 offset:9600
	v_cvt_pk_bf16_f32 v0, v137, s0
	ds_write_b16 v94, v0 offset:10128
	v_cvt_pk_bf16_f32 v0, v134, s0
	ds_write_b16 v94, v0 offset:16896
	v_cvt_pk_bf16_f32 v0, v135, s0
	ds_write_b16 v94, v0 offset:17424
	v_cvt_pk_bf16_f32 v0, v130, s0
	ds_write_b16 v94, v0 offset:17952
	v_cvt_pk_bf16_f32 v0, v131, s0
	ds_write_b16 v94, v0 offset:18480
	v_cvt_pk_bf16_f32 v0, v126, s0
	ds_write_b16 v94, v0 offset:16928
	v_cvt_pk_bf16_f32 v0, v127, s0
	ds_write_b16 v94, v0 offset:17456
	v_cvt_pk_bf16_f32 v0, v124, s0
	ds_write_b16 v94, v0 offset:17984
	v_cvt_pk_bf16_f32 v0, v125, s0
	ds_write_b16 v94, v0 offset:18512
	v_cvt_pk_bf16_f32 v0, v122, s0
	ds_write_b16 v94, v0 offset:16960
	v_cvt_pk_bf16_f32 v0, v123, s0
	ds_write_b16 v94, v0 offset:17488
	v_cvt_pk_bf16_f32 v0, v120, s0
	ds_write_b16 v94, v0 offset:18016
	v_cvt_pk_bf16_f32 v0, v121, s0
	ds_write_b16 v94, v0 offset:18544
	v_cvt_pk_bf16_f32 v0, v118, s0
	ds_write_b16 v94, v0 offset:16992
	v_cvt_pk_bf16_f32 v0, v119, s0
	ds_write_b16 v94, v0 offset:17520
	v_cvt_pk_bf16_f32 v0, v116, s0
	ds_write_b16 v94, v0 offset:18048
	v_cvt_pk_bf16_f32 v0, v117, s0
	ds_write_b16 v94, v0 offset:18576
	v_cvt_pk_bf16_f32 v0, v114, s0
	ds_write_b16 v94, v0 offset:25344
	v_cvt_pk_bf16_f32 v0, v115, s0
	ds_write_b16 v94, v0 offset:25872
	v_cvt_pk_bf16_f32 v0, v112, s0
	ds_write_b16 v94, v0 offset:26400
	v_cvt_pk_bf16_f32 v0, v113, s0
	ds_write_b16 v94, v0 offset:26928
	v_cvt_pk_bf16_f32 v0, v110, s0
	ds_write_b16 v94, v0 offset:25376
	v_cvt_pk_bf16_f32 v0, v111, s0
	ds_write_b16 v94, v0 offset:25904
	v_cvt_pk_bf16_f32 v0, v108, s0
	ds_write_b16 v94, v0 offset:26432
	v_cvt_pk_bf16_f32 v0, v109, s0
	ds_write_b16 v94, v0 offset:26960
	v_cvt_pk_bf16_f32 v0, v106, s0
	ds_write_b16 v94, v0 offset:25408
	v_cvt_pk_bf16_f32 v0, v107, s0
	ds_write_b16 v94, v0 offset:25936
	v_cvt_pk_bf16_f32 v0, v104, s0
	ds_write_b16 v94, v0 offset:26464
	v_cvt_pk_bf16_f32 v0, v105, s0
	ds_write_b16 v94, v0 offset:26992
	v_cvt_pk_bf16_f32 v0, v100, s0
	ds_write_b16 v94, v0 offset:25440
	v_cvt_pk_bf16_f32 v0, v101, s0
	ds_write_b16 v94, v0 offset:25968
	v_cvt_pk_bf16_f32 v0, v102, s0
	ds_write_b16 v94, v0 offset:26496
	v_cvt_pk_bf16_f32 v0, v103, s0
	v_mov_b32_e32 v38, v175
	v_readlane_b32 s12, v252, 38
	ds_write_b16 v94, v0 offset:27024
	s_waitcnt lgkmcnt(0)
	s_barrier
; #define RTID opaque_tid()
; __device__ __forceinline__ void phase_merge(const Params& p, u16* smem, volatile LAS unsigned* vb_) {
;     ...
;     const int tid3 = RTID;
; #pragma unroll
;     for (int k = 0; k < 8; ++k) {
;       const int c = tid3 + 512 * k;
;       const int row = c >> 5, ch = c & 31;
;       *(uint4*)(outp + (size_t)(mt * 128 + row) * 1024 + nt * 256 + ch * 8) = *(const uint4*)(smem + row * 264 + ch * 8);
;     }
;     __syncthreads();
;   }
	v_readlane_b32 s13, v252, 39
	v_lshlrev_b32_e32 v0, 4, v38
	s_add_u32 s12, s12, s42
	v_and_b32_e32 v0, 0x1f0, v0
	s_addc_u32 s13, s13, s43
	v_ashrrev_i32_e32 v28, 5, v38
	v_lshl_add_u64 v[34:35], s[12:13], 0, v[0:1]
	v_mad_u64_u32 v[26:27], s[12:13], v28, s2, v[0:1]
	v_add_u32_e32 v28, s22, v28
	v_ashrrev_i32_e32 v29, 31, v28
	v_lshlrev_b64 v[28:29], 11, v[28:29]
	v_lshl_add_u64 v[36:37], v[34:35], 0, v[28:29]
	ds_read_b128 v[26:29], v26
	v_add_u32_e32 v30, 0x200, v38
	v_ashrrev_i32_e32 v39, 5, v30
	v_mad_u64_u32 v[30:31], s[12:13], v39, s2, v[0:1]
	ds_read_b128 v[30:33], v30
	s_waitcnt lgkmcnt(1)
	global_store_dwordx4 v[36:37], v[26:29], off
	s_add_i32 s10, s10, s70
	s_and_b64 vcc, exec, s[0:1]
	v_add_u32_e32 v26, s22, v39
	v_ashrrev_i32_e32 v27, 31, v26
	v_lshlrev_b64 v[26:27], 11, v[26:27]
	v_lshl_add_u64 v[26:27], v[34:35], 0, v[26:27]
	s_waitcnt lgkmcnt(0)
	global_store_dwordx4 v[26:27], v[30:33], off
	v_add_u32_e32 v26, 0x400, v38
	v_ashrrev_i32_e32 v28, 5, v26
	v_mad_u64_u32 v[26:27], s[12:13], v28, s2, v[0:1]
	v_add_u32_e32 v28, s22, v28
	v_ashrrev_i32_e32 v29, 31, v28
	v_lshlrev_b64 v[28:29], 11, v[28:29]
	v_lshl_add_u64 v[36:37], v[34:35], 0, v[28:29]
	ds_read_b128 v[26:29], v26
	v_add_u32_e32 v30, 0x600, v38
	v_ashrrev_i32_e32 v39, 5, v30
	v_mad_u64_u32 v[30:31], s[12:13], v39, s2, v[0:1]
	ds_read_b128 v[30:33], v30
	s_waitcnt lgkmcnt(1)
	global_store_dwordx4 v[36:37], v[26:29], off
	s_nop 1
	v_add_u32_e32 v26, s22, v39
	v_ashrrev_i32_e32 v27, 31, v26
	v_lshlrev_b64 v[26:27], 11, v[26:27]
	v_lshl_add_u64 v[26:27], v[34:35], 0, v[26:27]
	s_waitcnt lgkmcnt(0)
	global_store_dwordx4 v[26:27], v[30:33], off
	v_add_u32_e32 v26, 0x800, v38
	v_ashrrev_i32_e32 v28, 5, v26
	v_mad_u64_u32 v[26:27], s[12:13], v28, s2, v[0:1]
	v_add_u32_e32 v28, s22, v28
	v_ashrrev_i32_e32 v29, 31, v28
	v_lshlrev_b64 v[28:29], 11, v[28:29]
	v_lshl_add_u64 v[36:37], v[34:35], 0, v[28:29]
	ds_read_b128 v[26:29], v26
	v_add_u32_e32 v30, 0xa00, v38
	v_ashrrev_i32_e32 v39, 5, v30
	v_mad_u64_u32 v[30:31], s[12:13], v39, s2, v[0:1]
	ds_read_b128 v[30:33], v30
	s_waitcnt lgkmcnt(1)
	global_store_dwordx4 v[36:37], v[26:29], off
	s_nop 1
	v_add_u32_e32 v26, s22, v39
	v_ashrrev_i32_e32 v27, 31, v26
	v_lshlrev_b64 v[26:27], 11, v[26:27]
	v_lshl_add_u64 v[26:27], v[34:35], 0, v[26:27]
	s_waitcnt lgkmcnt(0)
	global_store_dwordx4 v[26:27], v[30:33], off
	v_add_u32_e32 v26, 0xc00, v38
	v_ashrrev_i32_e32 v28, 5, v26
	v_mad_u64_u32 v[26:27], s[12:13], v28, s2, v[0:1]
	v_add_u32_e32 v28, s22, v28
	v_ashrrev_i32_e32 v29, 31, v28
	v_lshlrev_b64 v[28:29], 11, v[28:29]
	v_lshl_add_u64 v[36:37], v[34:35], 0, v[28:29]
	ds_read_b128 v[26:29], v26
	v_add_u32_e32 v30, 0xe00, v38
	v_ashrrev_i32_e32 v38, 5, v30
	v_mad_u64_u32 v[30:31], s[12:13], v38, s2, v[0:1]
	ds_read_b128 v[30:33], v30
	s_waitcnt lgkmcnt(1)
	global_store_dwordx4 v[36:37], v[26:29], off
	v_readlane_b32 s12, v254, 30
	s_add_i32 s21, s21, s12
	v_add_u32_e32 v26, s22, v38
	v_ashrrev_i32_e32 v27, 31, v26
	v_lshlrev_b64 v[26:27], 11, v[26:27]
	v_lshl_add_u64 v[26:27], v[34:35], 0, v[26:27]
	s_mov_b64 s[12:13], -1
	s_waitcnt lgkmcnt(0)
	global_store_dwordx4 v[26:27], v[30:33], off
	s_barrier
	s_cbranch_vccz .LBB0_22
